# same as previous plus the 8 wait states an MFMA result needs before the shortened chunk-max reads it (s_nop 3 on tile A blocks)
# speedup vs baseline: 1.0059x; 1.0059x over previous
; __device__ __forceinline__ void attn_item(const Params& p, unsigned char* lds, int item) {
;     ...
;         for (int ch = 0; ch < 8; ++ch) if (2 * ch < nkt) {
;             f32x4 sA[2], sB[2];
; #pragma unroll
;             for (int k4 = 0; k4 < 2; ++k4) { sA[k4] = (f32x4){0.f, 0.f, 0.f, 0.f}; sB[k4] = (f32x4){0.f, 0.f, 0.f, 0.f};
;                 if (2 * ch + k4 < nkt) { const unsigned char* ka = lds + AT_K + (16 * (2 * ch + k4) + qi) * 272 + 16 * g4;
; #pragma unroll
;                     for (int s = 0; s < 4; ++s) { const bf16x8 a = *(const bf16x8*)(ka + 64 * s);
;                         sA[k4] = __builtin_amdgcn_mfma_f32_16x16x32_bf16(a, bqA[s], sA[k4], 0, 0, 0); sB[k4] = __builtin_amdgcn_mfma_f32_16x16x32_bf16(a, bqB[s], sB[k4], 0, 0, 0); } } }
.LBB0_385:
	ds_read_b128 v[68:71], v214
	ds_read_b128 v[72:75], v214 offset:64
	s_xor_b64 s[12:13], s[12:13], -1
	v_cndmask_b32_e64 v0, 0, 1, s[12:13]
	s_mov_b64 s[18:19], -1
	s_waitcnt lgkmcnt(0)
	v_mfma_f32_16x16x32_bf16 v[76:79], v[68:71], v[64:67], 0
	v_cmp_ne_u32_e64 s[6:7], 1, v0
	s_andn2_b64 vcc, exec, s[12:13]
	v_mfma_f32_16x16x32_bf16 v[68:71], v[68:71], v[56:59], 0
	v_mfma_f32_16x16x32_bf16 v[76:79], v[72:75], v[60:63], v[76:79]
	v_mfma_f32_16x16x32_bf16 v[68:71], v[72:75], v[52:55], v[68:71]
	ds_read_b128 v[72:75], v214 offset:128
	ds_read_b128 v[80:83], v214 offset:192
	s_waitcnt lgkmcnt(1)
	v_mfma_f32_16x16x32_bf16 v[76:79], v[72:75], v[48:51], v[76:79]
	v_mfma_f32_16x16x32_bf16 v[68:71], v[72:75], v[40:43], v[68:71]
	s_waitcnt lgkmcnt(0)
	v_mfma_f32_16x16x32_bf16 v[76:79], v[80:83], v[44:47], v[76:79]
	v_mfma_f32_16x16x32_bf16 v[68:71], v[80:83], v[36:39], v[68:71]
	ds_read_b128 v[72:75], v214 offset:4352
	ds_read_b128 v[80:83], v214 offset:4416
	s_waitcnt lgkmcnt(1)
	v_mfma_f32_16x16x32_bf16 v[84:87], v[72:75], v[64:67], 0
	v_mfma_f32_16x16x32_bf16 v[72:75], v[72:75], v[56:59], 0
	s_waitcnt lgkmcnt(0)
	v_mfma_f32_16x16x32_bf16 v[84:87], v[80:83], v[60:63], v[84:87]
	v_mfma_f32_16x16x32_bf16 v[72:75], v[80:83], v[52:55], v[72:75]
	ds_read_b128 v[80:83], v214 offset:4480
	ds_read_b128 v[92:95], v214 offset:4544
	s_waitcnt lgkmcnt(1)
	v_mfma_f32_16x16x32_bf16 v[84:87], v[80:83], v[48:51], v[84:87]
	v_mfma_f32_16x16x32_bf16 v[72:75], v[80:83], v[40:43], v[72:75]
	s_waitcnt lgkmcnt(0)
	v_mfma_f32_16x16x32_bf16 v[80:83], v[92:95], v[44:47], v[84:87]
	v_mfma_f32_16x16x32_bf16 v[72:75], v[92:95], v[36:39], v[72:75]
	s_cbranch_vccnz .LBB0_387
	v_max3_f32 v0, v76, v77, v78
	v_max3_f32 v0, v0, v79, s95
	s_nop 3
	v_max3_f32 v2, v80, v81, v82
	v_max3_f32 v91, v0, v2, v83
	s_mov_b64 s[18:19], 0
	v_mov_b32_e32 v89, v83
	v_mov_b32_e32 v88, v82
	v_mov_b32_e32 v87, v81
	v_mov_b32_e32 v86, v80
	v_mov_b32_e32 v85, v79
	v_mov_b32_e32 v84, v78
	v_mov_b32_e32 v3, v77
	v_mov_b32_e32 v2, v76

; __device__ __forceinline__ void attn_item(const Params& p, unsigned char* lds, int item) {
;     ...
;         for (int ch = 0; ch < 8; ++ch) if (2 * ch < nkt) {
;             f32x4 sA[2], sB[2];
; #pragma unroll
;             for (int k4 = 0; k4 < 2; ++k4) { sA[k4] = (f32x4){0.f, 0.f, 0.f, 0.f}; sB[k4] = (f32x4){0.f, 0.f, 0.f, 0.f};
;                 if (2 * ch + k4 < nkt) { const unsigned char* ka = lds + AT_K + (16 * (2 * ch + k4) + qi) * 272 + 16 * g4;
; #pragma unroll
;                     for (int s = 0; s < 4; ++s) { const bf16x8 a = *(const bf16x8*)(ka + 64 * s);
;                         sA[k4] = __builtin_amdgcn_mfma_f32_16x16x32_bf16(a, bqA[s], sA[k4], 0, 0, 0); sB[k4] = __builtin_amdgcn_mfma_f32_16x16x32_bf16(a, bqB[s], sB[k4], 0, 0, 0); } } }
.LBB0_406:
	ds_read_b128 v[132:135], v206 offset:8704
	ds_read_b128 v[136:139], v206 offset:8768
	s_mov_b64 s[14:15], -1
	s_and_b64 vcc, exec, s[6:7]
	s_waitcnt lgkmcnt(1)
	v_mfma_f32_16x16x32_bf16 v[140:143], v[132:135], v[64:67], 0
	v_mfma_f32_16x16x32_bf16 v[132:135], v[132:135], v[56:59], 0
	s_waitcnt lgkmcnt(0)
	v_mfma_f32_16x16x32_bf16 v[140:143], v[136:139], v[60:63], v[140:143]
	v_mfma_f32_16x16x32_bf16 v[132:135], v[136:139], v[52:55], v[132:135]
	ds_read_b128 v[136:139], v206 offset:8832
	ds_read_b128 v[144:147], v206 offset:8896
	s_waitcnt lgkmcnt(1)
	v_mfma_f32_16x16x32_bf16 v[140:143], v[136:139], v[48:51], v[140:143]
	v_mfma_f32_16x16x32_bf16 v[132:135], v[136:139], v[40:43], v[132:135]
	s_waitcnt lgkmcnt(0)
	v_mfma_f32_16x16x32_bf16 v[140:143], v[144:147], v[44:47], v[140:143]
	v_mfma_f32_16x16x32_bf16 v[132:135], v[144:147], v[36:39], v[132:135]
	ds_read_b128 v[136:139], v206 offset:13056
	ds_read_b128 v[144:147], v206 offset:13120
	s_waitcnt lgkmcnt(1)
	v_mfma_f32_16x16x32_bf16 v[188:191], v[136:139], v[64:67], 0
	v_mfma_f32_16x16x32_bf16 v[136:139], v[136:139], v[56:59], 0
	s_waitcnt lgkmcnt(0)
	v_mfma_f32_16x16x32_bf16 v[188:191], v[144:147], v[60:63], v[188:191]
	v_mfma_f32_16x16x32_bf16 v[136:139], v[144:147], v[52:55], v[136:139]
	ds_read_b128 v[144:147], v206 offset:13184
	ds_read_b128 v[244:247], v206 offset:13248
	s_waitcnt lgkmcnt(1)
	v_mfma_f32_16x16x32_bf16 v[188:191], v[144:147], v[48:51], v[188:191]
	v_mfma_f32_16x16x32_bf16 v[136:139], v[144:147], v[40:43], v[136:139]
	s_waitcnt lgkmcnt(0)
	v_mfma_f32_16x16x32_bf16 v[144:147], v[244:247], v[44:47], v[188:191]
	v_mfma_f32_16x16x32_bf16 v[136:139], v[244:247], v[36:39], v[136:139]
	s_cbranch_vccnz .LBB0_408
	v_max3_f32 v2, v140, v141, v142
	v_max3_f32 v2, v2, v143, s95
	s_nop 3
	v_max3_f32 v3, v144, v145, v146
	v_max3_f32 v243, v2, v3, v147
	s_mov_b64 s[14:15], 0
	v_mov_b32_e32 v193, v147
	v_mov_b32_e32 v192, v146
	v_mov_b32_e32 v191, v145
	v_mov_b32_e32 v190, v144
	v_mov_b32_e32 v189, v143
	v_mov_b32_e32 v188, v142
	v_mov_b32_e32 v3, v141
	v_mov_b32_e32 v2, v140

; __device__ __forceinline__ void attn_item(const Params& p, unsigned char* lds, int item) {
;     ...
;         for (int ch = 0; ch < 8; ++ch) if (2 * ch < nkt) {
;             f32x4 sA[2], sB[2];
; #pragma unroll
;             for (int k4 = 0; k4 < 2; ++k4) { sA[k4] = (f32x4){0.f, 0.f, 0.f, 0.f}; sB[k4] = (f32x4){0.f, 0.f, 0.f, 0.f};
;                 if (2 * ch + k4 < nkt) { const unsigned char* ka = lds + AT_K + (16 * (2 * ch + k4) + qi) * 272 + 16 * g4;
; #pragma unroll
;                     for (int s = 0; s < 4; ++s) { const bf16x8 a = *(const bf16x8*)(ka + 64 * s);
;                         sA[k4] = __builtin_amdgcn_mfma_f32_16x16x32_bf16(a, bqA[s], sA[k4], 0, 0, 0); sB[k4] = __builtin_amdgcn_mfma_f32_16x16x32_bf16(a, bqB[s], sB[k4], 0, 0, 0); } } }
.LBB0_425:
	ds_read_b128 v[132:135], v206 offset:17408
	ds_read_b128 v[136:139], v206 offset:17472
	s_mov_b64 s[14:15], -1
	s_and_b64 vcc, exec, s[6:7]
	s_waitcnt lgkmcnt(1)
	v_mfma_f32_16x16x32_bf16 v[140:143], v[132:135], v[64:67], 0
	v_mfma_f32_16x16x32_bf16 v[132:135], v[132:135], v[56:59], 0
	s_waitcnt lgkmcnt(0)
	v_mfma_f32_16x16x32_bf16 v[140:143], v[136:139], v[60:63], v[140:143]
	v_mfma_f32_16x16x32_bf16 v[132:135], v[136:139], v[52:55], v[132:135]
	ds_read_b128 v[136:139], v206 offset:17536
	ds_read_b128 v[144:147], v206 offset:17600
	s_waitcnt lgkmcnt(1)
	v_mfma_f32_16x16x32_bf16 v[140:143], v[136:139], v[48:51], v[140:143]
	v_mfma_f32_16x16x32_bf16 v[132:135], v[136:139], v[40:43], v[132:135]
	s_waitcnt lgkmcnt(0)
	v_mfma_f32_16x16x32_bf16 v[140:143], v[144:147], v[44:47], v[140:143]
	v_mfma_f32_16x16x32_bf16 v[132:135], v[144:147], v[36:39], v[132:135]
	ds_read_b128 v[136:139], v206 offset:21760
	ds_read_b128 v[144:147], v206 offset:21824
	s_waitcnt lgkmcnt(1)
	v_mfma_f32_16x16x32_bf16 v[188:191], v[136:139], v[64:67], 0
	v_mfma_f32_16x16x32_bf16 v[136:139], v[136:139], v[56:59], 0
	s_waitcnt lgkmcnt(0)
	v_mfma_f32_16x16x32_bf16 v[188:191], v[144:147], v[60:63], v[188:191]
	v_mfma_f32_16x16x32_bf16 v[136:139], v[144:147], v[52:55], v[136:139]
	ds_read_b128 v[144:147], v206 offset:21888
	ds_read_b128 v[244:247], v206 offset:21952
	s_waitcnt lgkmcnt(1)
	v_mfma_f32_16x16x32_bf16 v[188:191], v[144:147], v[48:51], v[188:191]
	v_mfma_f32_16x16x32_bf16 v[136:139], v[144:147], v[40:43], v[136:139]
	s_waitcnt lgkmcnt(0)
	v_mfma_f32_16x16x32_bf16 v[144:147], v[244:247], v[44:47], v[188:191]
	v_mfma_f32_16x16x32_bf16 v[136:139], v[244:247], v[36:39], v[136:139]
	s_cbranch_vccnz .LBB0_427
	v_max3_f32 v2, v140, v141, v142
	v_max3_f32 v2, v2, v143, s95
	s_nop 3
	v_max3_f32 v3, v144, v145, v146
	v_max3_f32 v243, v2, v3, v147
	s_mov_b64 s[14:15], 0
	v_mov_b32_e32 v193, v147
	v_mov_b32_e32 v192, v146
	v_mov_b32_e32 v191, v145
	v_mov_b32_e32 v190, v144
	v_mov_b32_e32 v189, v143
	v_mov_b32_e32 v188, v142
	v_mov_b32_e32 v3, v141
	v_mov_b32_e32 v2, v140

; __device__ __forceinline__ void attn_item(const Params& p, unsigned char* lds, int item) {
;     ...
;         for (int ch = 0; ch < 8; ++ch) if (2 * ch < nkt) {
;             f32x4 sA[2], sB[2];
; #pragma unroll
;             for (int k4 = 0; k4 < 2; ++k4) { sA[k4] = (f32x4){0.f, 0.f, 0.f, 0.f}; sB[k4] = (f32x4){0.f, 0.f, 0.f, 0.f};
;                 if (2 * ch + k4 < nkt) { const unsigned char* ka = lds + AT_K + (16 * (2 * ch + k4) + qi) * 272 + 16 * g4;
; #pragma unroll
;                     for (int s = 0; s < 4; ++s) { const bf16x8 a = *(const bf16x8*)(ka + 64 * s);
;                         sA[k4] = __builtin_amdgcn_mfma_f32_16x16x32_bf16(a, bqA[s], sA[k4], 0, 0, 0); sB[k4] = __builtin_amdgcn_mfma_f32_16x16x32_bf16(a, bqB[s], sB[k4], 0, 0, 0); } } }
.LBB0_444:
	ds_read_b128 v[132:135], v206 offset:26112
	ds_read_b128 v[136:139], v206 offset:26176
	s_mov_b64 s[14:15], -1
	s_and_b64 vcc, exec, s[6:7]
	s_waitcnt lgkmcnt(1)
	v_mfma_f32_16x16x32_bf16 v[140:143], v[132:135], v[64:67], 0
	v_mfma_f32_16x16x32_bf16 v[132:135], v[132:135], v[56:59], 0
	s_waitcnt lgkmcnt(0)
	v_mfma_f32_16x16x32_bf16 v[140:143], v[136:139], v[60:63], v[140:143]
	v_mfma_f32_16x16x32_bf16 v[132:135], v[136:139], v[52:55], v[132:135]
	ds_read_b128 v[136:139], v206 offset:26240
	ds_read_b128 v[144:147], v206 offset:26304
	s_waitcnt lgkmcnt(1)
	v_mfma_f32_16x16x32_bf16 v[140:143], v[136:139], v[48:51], v[140:143]
	v_mfma_f32_16x16x32_bf16 v[132:135], v[136:139], v[40:43], v[132:135]
	s_waitcnt lgkmcnt(0)
	v_mfma_f32_16x16x32_bf16 v[140:143], v[144:147], v[44:47], v[140:143]
	v_mfma_f32_16x16x32_bf16 v[132:135], v[144:147], v[36:39], v[132:135]
	ds_read_b128 v[136:139], v206 offset:30464
	ds_read_b128 v[144:147], v206 offset:30528
	s_waitcnt lgkmcnt(1)
	v_mfma_f32_16x16x32_bf16 v[188:191], v[136:139], v[64:67], 0
	v_mfma_f32_16x16x32_bf16 v[136:139], v[136:139], v[56:59], 0
	s_waitcnt lgkmcnt(0)
	v_mfma_f32_16x16x32_bf16 v[188:191], v[144:147], v[60:63], v[188:191]
	v_mfma_f32_16x16x32_bf16 v[136:139], v[144:147], v[52:55], v[136:139]
	ds_read_b128 v[144:147], v206 offset:30592
	ds_read_b128 v[244:247], v206 offset:30656
	s_waitcnt lgkmcnt(1)
	v_mfma_f32_16x16x32_bf16 v[188:191], v[144:147], v[48:51], v[188:191]
	v_mfma_f32_16x16x32_bf16 v[136:139], v[144:147], v[40:43], v[136:139]
	s_waitcnt lgkmcnt(0)
	v_mfma_f32_16x16x32_bf16 v[144:147], v[244:247], v[44:47], v[188:191]
	v_mfma_f32_16x16x32_bf16 v[136:139], v[244:247], v[36:39], v[136:139]
	s_cbranch_vccnz .LBB0_446
	v_max3_f32 v2, v140, v141, v142
	v_max3_f32 v2, v2, v143, s95
	s_nop 3
	v_max3_f32 v3, v144, v145, v146
	v_max3_f32 v243, v2, v3, v147
	s_mov_b64 s[14:15], 0
	v_mov_b32_e32 v193, v147
	v_mov_b32_e32 v192, v146
	v_mov_b32_e32 v191, v145
	v_mov_b32_e32 v190, v144
	v_mov_b32_e32 v189, v143
	v_mov_b32_e32 v188, v142
	v_mov_b32_e32 v3, v141
	v_mov_b32_e32 v2, v140

; __device__ __forceinline__ void attn_item(const Params& p, unsigned char* lds, int item) {
;     ...
;         for (int ch = 0; ch < 8; ++ch) if (2 * ch < nkt) {
;             f32x4 sA[2], sB[2];
; #pragma unroll
;             for (int k4 = 0; k4 < 2; ++k4) { sA[k4] = (f32x4){0.f, 0.f, 0.f, 0.f}; sB[k4] = (f32x4){0.f, 0.f, 0.f, 0.f};
;                 if (2 * ch + k4 < nkt) { const unsigned char* ka = lds + AT_K + (16 * (2 * ch + k4) + qi) * 272 + 16 * g4;
; #pragma unroll
;                     for (int s = 0; s < 4; ++s) { const bf16x8 a = *(const bf16x8*)(ka + 64 * s);
;                         sA[k4] = __builtin_amdgcn_mfma_f32_16x16x32_bf16(a, bqA[s], sA[k4], 0, 0, 0); sB[k4] = __builtin_amdgcn_mfma_f32_16x16x32_bf16(a, bqB[s], sB[k4], 0, 0, 0); } } }
.LBB0_463:
	ds_read_b128 v[132:135], v206 offset:34816
	ds_read_b128 v[136:139], v206 offset:34880
	s_mov_b64 s[14:15], -1
	s_and_b64 vcc, exec, s[6:7]
	s_waitcnt lgkmcnt(1)
	v_mfma_f32_16x16x32_bf16 v[140:143], v[132:135], v[64:67], 0
	v_mfma_f32_16x16x32_bf16 v[132:135], v[132:135], v[56:59], 0
	s_waitcnt lgkmcnt(0)
	v_mfma_f32_16x16x32_bf16 v[140:143], v[136:139], v[60:63], v[140:143]
	v_mfma_f32_16x16x32_bf16 v[132:135], v[136:139], v[52:55], v[132:135]
	ds_read_b128 v[136:139], v206 offset:34944
	ds_read_b128 v[144:147], v206 offset:35008
	s_waitcnt lgkmcnt(1)
	v_mfma_f32_16x16x32_bf16 v[140:143], v[136:139], v[48:51], v[140:143]
	v_mfma_f32_16x16x32_bf16 v[132:135], v[136:139], v[40:43], v[132:135]
	s_waitcnt lgkmcnt(0)
	v_mfma_f32_16x16x32_bf16 v[140:143], v[144:147], v[44:47], v[140:143]
	v_mfma_f32_16x16x32_bf16 v[132:135], v[144:147], v[36:39], v[132:135]
	ds_read_b128 v[136:139], v206 offset:39168
	ds_read_b128 v[144:147], v206 offset:39232
	s_waitcnt lgkmcnt(1)
	v_mfma_f32_16x16x32_bf16 v[188:191], v[136:139], v[64:67], 0
	v_mfma_f32_16x16x32_bf16 v[136:139], v[136:139], v[56:59], 0
	s_waitcnt lgkmcnt(0)
	v_mfma_f32_16x16x32_bf16 v[188:191], v[144:147], v[60:63], v[188:191]
	v_mfma_f32_16x16x32_bf16 v[136:139], v[144:147], v[52:55], v[136:139]
	ds_read_b128 v[144:147], v206 offset:39296
	ds_read_b128 v[244:247], v206 offset:39360
	s_waitcnt lgkmcnt(1)
	v_mfma_f32_16x16x32_bf16 v[188:191], v[144:147], v[48:51], v[188:191]
	v_mfma_f32_16x16x32_bf16 v[136:139], v[144:147], v[40:43], v[136:139]
	s_waitcnt lgkmcnt(0)
	v_mfma_f32_16x16x32_bf16 v[144:147], v[244:247], v[44:47], v[188:191]
	v_mfma_f32_16x16x32_bf16 v[136:139], v[244:247], v[36:39], v[136:139]
	s_cbranch_vccnz .LBB0_465
	v_max3_f32 v2, v140, v141, v142
	v_max3_f32 v2, v2, v143, s95
	s_nop 3
	v_max3_f32 v3, v144, v145, v146
	v_max3_f32 v243, v2, v3, v147
	s_mov_b64 s[14:15], 0
	v_mov_b32_e32 v193, v147
	v_mov_b32_e32 v192, v146
	v_mov_b32_e32 v191, v145
	v_mov_b32_e32 v190, v144
	v_mov_b32_e32 v189, v143
	v_mov_b32_e32 v188, v142
	v_mov_b32_e32 v3, v141
	v_mov_b32_e32 v2, v140

; __device__ __forceinline__ void attn_item(const Params& p, unsigned char* lds, int item) {
;     ...
;         for (int ch = 0; ch < 8; ++ch) if (2 * ch < nkt) {
;             f32x4 sA[2], sB[2];
; #pragma unroll
;             for (int k4 = 0; k4 < 2; ++k4) { sA[k4] = (f32x4){0.f, 0.f, 0.f, 0.f}; sB[k4] = (f32x4){0.f, 0.f, 0.f, 0.f};
;                 if (2 * ch + k4 < nkt) { const unsigned char* ka = lds + AT_K + (16 * (2 * ch + k4) + qi) * 272 + 16 * g4;
; #pragma unroll
;                     for (int s = 0; s < 4; ++s) { const bf16x8 a = *(const bf16x8*)(ka + 64 * s);
;                         sA[k4] = __builtin_amdgcn_mfma_f32_16x16x32_bf16(a, bqA[s], sA[k4], 0, 0, 0); sB[k4] = __builtin_amdgcn_mfma_f32_16x16x32_bf16(a, bqB[s], sB[k4], 0, 0, 0); } } }
.LBB0_482:
	ds_read_b128 v[132:135], v206 offset:43520
	ds_read_b128 v[136:139], v206 offset:43584
	s_mov_b64 s[14:15], -1
	s_and_b64 vcc, exec, s[6:7]
	s_waitcnt lgkmcnt(1)
	v_mfma_f32_16x16x32_bf16 v[140:143], v[132:135], v[64:67], 0
	v_mfma_f32_16x16x32_bf16 v[132:135], v[132:135], v[56:59], 0
	s_waitcnt lgkmcnt(0)
	v_mfma_f32_16x16x32_bf16 v[140:143], v[136:139], v[60:63], v[140:143]
	v_mfma_f32_16x16x32_bf16 v[132:135], v[136:139], v[52:55], v[132:135]
	ds_read_b128 v[136:139], v206 offset:43648
	ds_read_b128 v[144:147], v206 offset:43712
	s_waitcnt lgkmcnt(1)
	v_mfma_f32_16x16x32_bf16 v[140:143], v[136:139], v[48:51], v[140:143]
	v_mfma_f32_16x16x32_bf16 v[132:135], v[136:139], v[40:43], v[132:135]
	s_waitcnt lgkmcnt(0)
	v_mfma_f32_16x16x32_bf16 v[140:143], v[144:147], v[44:47], v[140:143]
	v_mfma_f32_16x16x32_bf16 v[132:135], v[144:147], v[36:39], v[132:135]
	ds_read_b128 v[136:139], v206 offset:47872
	ds_read_b128 v[144:147], v206 offset:47936
	s_waitcnt lgkmcnt(1)
	v_mfma_f32_16x16x32_bf16 v[188:191], v[136:139], v[64:67], 0
	v_mfma_f32_16x16x32_bf16 v[136:139], v[136:139], v[56:59], 0
	s_waitcnt lgkmcnt(0)
	v_mfma_f32_16x16x32_bf16 v[188:191], v[144:147], v[60:63], v[188:191]
	v_mfma_f32_16x16x32_bf16 v[136:139], v[144:147], v[52:55], v[136:139]
	ds_read_b128 v[144:147], v206 offset:48000
	ds_read_b128 v[244:247], v206 offset:48064
	s_waitcnt lgkmcnt(1)
	v_mfma_f32_16x16x32_bf16 v[188:191], v[144:147], v[48:51], v[188:191]
	v_mfma_f32_16x16x32_bf16 v[136:139], v[144:147], v[40:43], v[136:139]
	s_waitcnt lgkmcnt(0)
	v_mfma_f32_16x16x32_bf16 v[144:147], v[244:247], v[44:47], v[188:191]
	v_mfma_f32_16x16x32_bf16 v[136:139], v[244:247], v[36:39], v[136:139]
	s_cbranch_vccnz .LBB0_484
	v_max3_f32 v2, v140, v141, v142
	v_max3_f32 v2, v2, v143, s95
	s_nop 3
	v_max3_f32 v3, v144, v145, v146
	v_max3_f32 v243, v2, v3, v147
	s_mov_b64 s[14:15], 0
	v_mov_b32_e32 v193, v147
	v_mov_b32_e32 v192, v146
	v_mov_b32_e32 v191, v145
	v_mov_b32_e32 v190, v144
	v_mov_b32_e32 v189, v143
	v_mov_b32_e32 v188, v142
	v_mov_b32_e32 v3, v141
	v_mov_b32_e32 v2, v140

; __device__ __forceinline__ void attn_item(const Params& p, unsigned char* lds, int item) {
;     ...
;         for (int ch = 0; ch < 8; ++ch) if (2 * ch < nkt) {
;             f32x4 sA[2], sB[2];
; #pragma unroll
;             for (int k4 = 0; k4 < 2; ++k4) { sA[k4] = (f32x4){0.f, 0.f, 0.f, 0.f}; sB[k4] = (f32x4){0.f, 0.f, 0.f, 0.f};
;                 if (2 * ch + k4 < nkt) { const unsigned char* ka = lds + AT_K + (16 * (2 * ch + k4) + qi) * 272 + 16 * g4;
; #pragma unroll
;                     for (int s = 0; s < 4; ++s) { const bf16x8 a = *(const bf16x8*)(ka + 64 * s);
;                         sA[k4] = __builtin_amdgcn_mfma_f32_16x16x32_bf16(a, bqA[s], sA[k4], 0, 0, 0); sB[k4] = __builtin_amdgcn_mfma_f32_16x16x32_bf16(a, bqB[s], sB[k4], 0, 0, 0); } } }
.LBB0_501:
	ds_read_b128 v[132:135], v206 offset:52224
	ds_read_b128 v[136:139], v206 offset:52288
	s_mov_b64 s[14:15], -1
	s_and_b64 vcc, exec, s[6:7]
	s_waitcnt lgkmcnt(1)
	v_mfma_f32_16x16x32_bf16 v[140:143], v[132:135], v[64:67], 0
	v_mfma_f32_16x16x32_bf16 v[132:135], v[132:135], v[56:59], 0
	s_waitcnt lgkmcnt(0)
	v_mfma_f32_16x16x32_bf16 v[140:143], v[136:139], v[60:63], v[140:143]
	v_mfma_f32_16x16x32_bf16 v[132:135], v[136:139], v[52:55], v[132:135]
	ds_read_b128 v[136:139], v206 offset:52352
	ds_read_b128 v[144:147], v206 offset:52416
	s_waitcnt lgkmcnt(1)
	v_mfma_f32_16x16x32_bf16 v[140:143], v[136:139], v[48:51], v[140:143]
	v_mfma_f32_16x16x32_bf16 v[132:135], v[136:139], v[40:43], v[132:135]
	s_waitcnt lgkmcnt(0)
	v_mfma_f32_16x16x32_bf16 v[140:143], v[144:147], v[44:47], v[140:143]
	v_mfma_f32_16x16x32_bf16 v[132:135], v[144:147], v[36:39], v[132:135]
	ds_read_b128 v[136:139], v206 offset:56576
	ds_read_b128 v[144:147], v206 offset:56640
	s_waitcnt lgkmcnt(1)
	v_mfma_f32_16x16x32_bf16 v[188:191], v[136:139], v[64:67], 0
	v_mfma_f32_16x16x32_bf16 v[136:139], v[136:139], v[56:59], 0
	s_waitcnt lgkmcnt(0)
	v_mfma_f32_16x16x32_bf16 v[188:191], v[144:147], v[60:63], v[188:191]
	v_mfma_f32_16x16x32_bf16 v[136:139], v[144:147], v[52:55], v[136:139]
	ds_read_b128 v[144:147], v206 offset:56704
	ds_read_b128 v[244:247], v206 offset:56768
	s_waitcnt lgkmcnt(1)
	v_mfma_f32_16x16x32_bf16 v[188:191], v[144:147], v[48:51], v[188:191]
	v_mfma_f32_16x16x32_bf16 v[136:139], v[144:147], v[40:43], v[136:139]
	s_waitcnt lgkmcnt(0)
	v_mfma_f32_16x16x32_bf16 v[144:147], v[244:247], v[44:47], v[188:191]
	v_mfma_f32_16x16x32_bf16 v[136:139], v[244:247], v[36:39], v[136:139]
	s_cbranch_vccnz .LBB0_503
	v_max3_f32 v2, v140, v141, v142
	v_max3_f32 v2, v2, v143, s95
	s_nop 3
	v_max3_f32 v3, v144, v145, v146
	v_max3_f32 v243, v2, v3, v147
	s_mov_b64 s[14:15], 0
	v_mov_b32_e32 v193, v147
	v_mov_b32_e32 v192, v146
	v_mov_b32_e32 v191, v145
	v_mov_b32_e32 v190, v144
	v_mov_b32_e32 v189, v143
	v_mov_b32_e32 v188, v142
	v_mov_b32_e32 v3, v141
	v_mov_b32_e32 v2, v140

; __device__ __forceinline__ void attn_item(const Params& p, unsigned char* lds, int item) {
;     ...
;         for (int ch = 0; ch < 8; ++ch) if (2 * ch < nkt) {
;             f32x4 sA[2], sB[2];
; #pragma unroll
;             for (int k4 = 0; k4 < 2; ++k4) { sA[k4] = (f32x4){0.f, 0.f, 0.f, 0.f}; sB[k4] = (f32x4){0.f, 0.f, 0.f, 0.f};
;                 if (2 * ch + k4 < nkt) { const unsigned char* ka = lds + AT_K + (16 * (2 * ch + k4) + qi) * 272 + 16 * g4;
; #pragma unroll
;                     for (int s = 0; s < 4; ++s) { const bf16x8 a = *(const bf16x8*)(ka + 64 * s);
;                         sA[k4] = __builtin_amdgcn_mfma_f32_16x16x32_bf16(a, bqA[s], sA[k4], 0, 0, 0); sB[k4] = __builtin_amdgcn_mfma_f32_16x16x32_bf16(a, bqB[s], sB[k4], 0, 0, 0); } } }
.LBB0_520:
	ds_read_b128 v[132:135], v206 offset:60928
	ds_read_b128 v[136:139], v206 offset:60992
	s_mov_b64 s[10:11], -1
	s_and_b64 vcc, exec, s[6:7]
	s_waitcnt lgkmcnt(1)
	v_mfma_f32_16x16x32_bf16 v[140:143], v[132:135], v[64:67], 0
	v_mfma_f32_16x16x32_bf16 v[132:135], v[132:135], v[56:59], 0
	s_waitcnt lgkmcnt(0)
	v_mfma_f32_16x16x32_bf16 v[140:143], v[136:139], v[60:63], v[140:143]
	v_mfma_f32_16x16x32_bf16 v[132:135], v[136:139], v[52:55], v[132:135]
	ds_read_b128 v[136:139], v206 offset:61056
	ds_read_b128 v[144:147], v206 offset:61120
	s_waitcnt lgkmcnt(1)
	v_mfma_f32_16x16x32_bf16 v[140:143], v[136:139], v[48:51], v[140:143]
	v_mfma_f32_16x16x32_bf16 v[132:135], v[136:139], v[40:43], v[132:135]
	s_waitcnt lgkmcnt(0)
	v_mfma_f32_16x16x32_bf16 v[136:139], v[144:147], v[44:47], v[140:143]
	v_mfma_f32_16x16x32_bf16 v[132:135], v[144:147], v[36:39], v[132:135]
	s_nop 3
	ds_read_b128 v[140:143], v206 offset:65280
	ds_read_b128 v[144:147], v206 offset:65344
	s_waitcnt lgkmcnt(1)
	v_mfma_f32_16x16x32_bf16 v[64:67], v[140:143], v[64:67], 0
	v_mfma_f32_16x16x32_bf16 v[56:59], v[140:143], v[56:59], 0
	s_waitcnt lgkmcnt(0)
	v_mfma_f32_16x16x32_bf16 v[60:63], v[144:147], v[60:63], v[64:67]
	v_mfma_f32_16x16x32_bf16 v[52:55], v[144:147], v[52:55], v[56:59]
	s_nop 4
	ds_read_b128 v[56:59], v206 offset:65408
	ds_read_b128 v[64:67], v206 offset:65472
	s_waitcnt lgkmcnt(1)
	v_mfma_f32_16x16x32_bf16 v[48:51], v[56:59], v[48:51], v[60:63]
	v_mfma_f32_16x16x32_bf16 v[52:55], v[56:59], v[40:43], v[52:55]
	s_waitcnt lgkmcnt(0)
	v_mfma_f32_16x16x32_bf16 v[40:43], v[64:67], v[44:47], v[48:51]
	v_mfma_f32_16x16x32_bf16 v[36:39], v[64:67], v[36:39], v[52:55]
	s_cbranch_vccnz .LBB0_522
	v_max3_f32 v2, v136, v137, v138
	v_max3_f32 v2, v2, v139, s95
	s_nop 3
	v_max3_f32 v3, v40, v41, v42
	v_max3_f32 v50, v2, v3, v43
	s_mov_b64 s[10:11], 0
	v_mov_b32_e32 v45, v43
	v_mov_b32_e32 v44, v42
	v_mov_b32_e32 v3, v41
	v_mov_b32_e32 v2, v40
	v_mov_b32_e32 v47, v139
	v_mov_b32_e32 v46, v138
	v_mov_b32_e32 v49, v137
	v_mov_b32_e32 v48, v136
